# attention tile loop: 22 packed v_pk_mul_f32 split into scalar v_mul_f32 pairs (instruction-selection lever), on top of the K-fragment prefetch version
# baseline (speedup 1.0000x reference)
.LBB0_545:
	s_add_i32 s72, s87, s59
	v_mov_b32_e32 v195, v131
	s_cmp_lt_i32 s72, s58
	s_mov_b32 s72, s93
	s_cbranch_scc1 .LBB0_544
	s_add_i32 s80, s87, s77
	s_lshr_b32 s80, s80, 2
	v_bitop3_b32 v6, s80, v142, v1 bitop3:0x36
	v_lshlrev_b32_e32 v28, 3, v6
	v_or_b32_e32 v27, s80, v1
	s_waitcnt lgkmcnt(0)
	v_mfma_f32_32x32x16_bf16 v[2:17], v[240:243], v[114:117], 0
	v_bitop3_b32 v22, v27, v142, 2 bitop3:0x36
	v_lshlrev_b32_e32 v30, 3, v22
	v_bitop3_b32 v22, v27, v142, 4 bitop3:0x36
	v_lshlrev_b32_e32 v32, 3, v22
	s_waitcnt lgkmcnt(1)
	v_mfma_f32_32x32x16_bf16 v[2:17], v[244:247], v[118:121], v[2:17]
	v_bitop3_b32 v18, v27, v142, 6 bitop3:0x36
	v_lshlrev_b32_e32 v27, 3, v18
	v_add_u32_e32 v29, v202, v28
	v_add_u32_e32 v132, v202, v27
	s_waitcnt lgkmcnt(1)
	v_mfma_f32_32x32x16_bf16 v[2:17], v[248:251], v[122:125], v[2:17]
	v_add_u32_e32 v22, v203, v28
	v_add_u32_e32 v31, v202, v30
	v_add_u32_e32 v33, v202, v32
	ds_read_b64 v[138:139], v29 offset:49152
	ds_read_b64 v[140:141], v31 offset:49152
	ds_read_b64 v[130:131], v33 offset:49152
	ds_read_b64 v[132:133], v132 offset:49152
	v_add_u32_e32 v23, v203, v30
	v_add_u32_e32 v24, v203, v32
	v_add_u32_e32 v25, v203, v27
	s_waitcnt lgkmcnt(4)
	v_mfma_f32_32x32x16_bf16 v[2:17], v[252:255], v[126:129], v[2:17]
	ds_read_b64 v[218:219], v22 offset:24576
	ds_read_b64 v[220:221], v23 offset:24576
	ds_read_b64 v[134:135], v24 offset:24576
	ds_read_b64 v[136:137], v25 offset:24576
	s_add_i32 s90, s90, -1
	s_nop 6
	v_min_f32_e64 v3, -v3, s98
	v_exp_f32_e32 v3, v3
	v_min_f32_e64 v5, -v5, s98
	v_min_f32_e64 v4, -v4, s98
	v_add_f32_e32 v19, 1.0, v3
	v_exp_f32_e32 v194, v5
	v_min_f32_e64 v5, -v6, s98
	v_rcp_f32_e32 v169, v19
	v_exp_f32_e32 v4, v4
	v_exp_f32_e32 v6, v5
	v_min_f32_e64 v5, -v7, s98
	v_exp_f32_e32 v7, v5
	v_mul_f32_e32 v20, v3, v169
	v_add_f32_e32 v3, 1.0, v4
	v_rcp_f32_e32 v22, v3
	v_add_f32_e32 v3, 1.0, v194
	v_rcp_f32_e32 v24, v3
	v_add_f32_e32 v3, 1.0, v6
	v_rcp_f32_e32 v26, v3
	v_add_f32_e32 v3, 1.0, v7
	v_rcp_f32_e32 v27, v3
	v_min_f32_e64 v3, -v8, s98
	v_exp_f32_e32 v8, v3
	v_min_f32_e64 v3, -v9, s98
	v_exp_f32_e32 v9, v3
	v_add_f32_e32 v3, 1.0, v8
	v_rcp_f32_e32 v28, v3
	v_min_f32_e64 v5, -v12, s98
	v_add_f32_e32 v3, 1.0, v9
	v_rcp_f32_e32 v29, v3
	v_min_f32_e64 v3, -v10, s98
	v_exp_f32_e32 v10, v3
	v_min_f32_e64 v3, -v11, s98
	v_exp_f32_e32 v11, v5
	v_min_f32_e64 v5, -v13, s98
	v_exp_f32_e32 v31, v5
	v_min_f32_e64 v5, -v14, s98
	v_exp_f32_e32 v30, v3
	v_exp_f32_e32 v12, v5
	v_min_f32_e64 v5, -v15, s98
	v_exp_f32_e32 v14, v5
	v_min_f32_e64 v5, -v16, s98
	v_add_f32_e32 v3, 1.0, v10
	v_rcp_f32_e32 v226, v3
	v_add_f32_e32 v3, 1.0, v30
	v_exp_f32_e32 v13, v5
	v_min_f32_e64 v5, -v17, s98
	v_rcp_f32_e32 v228, v3
	v_add_f32_e32 v3, 1.0, v11
	v_rcp_f32_e32 v227, v3
	v_add_f32_e32 v3, 1.0, v31
	v_exp_f32_e32 v15, v5
	v_rcp_f32_e32 v229, v3
	v_add_f32_e32 v3, 1.0, v12
	v_rcp_f32_e32 v230, v3
	v_add_f32_e32 v3, 1.0, v14
	v_rcp_f32_e32 v16, v3
	v_add_f32_e32 v3, 1.0, v13
	v_rcp_f32_e32 v231, v3
	v_add_f32_e32 v3, 1.0, v15
	v_rcp_f32_e32 v17, v3
	v_min_f32_e64 v2, -v2, s98
	v_exp_f32_e32 v2, v2
	v_mul_f32_e32 v12, v12, v230
	v_mul_f32_e32 v13, v13, v231
	v_mul_f32_e32 v14, v14, v16
	v_mul_f32_e32 v15, v15, v17
	v_mul_f32_e32 v6, v6, v26
	v_mul_f32_e32 v7, v7, v27
	v_mul_f32_e32 v224, v12, v14
	v_mul_f32_e32 v225, v13, v15
	v_add_f32_e32 v18, 1.0, v2
	v_mul_f32_e32 v3, v224, v225
	v_mov_b32_e32 v238, v3
	v_mov_b32_e32 v5, v3
	s_nop 1
	v_permlane32_swap_b32_e32 v238, v5
	s_nop 0
	v_cndmask_b32_e64 v5, v238, v5, s[0:1]
	v_rcp_f32_e32 v18, v18
	v_mul_f32_e32 v8, v8, v28
	v_mul_f32_e32 v9, v9, v29
	v_mul_f32_e32 v10, v10, v226
	v_mul_f32_e32 v11, v11, v227
	v_mul_f32_e32 v232, v30, v228
	v_mul_f32_e32 v233, v31, v229
	v_mul_f32_e32 v32, v6, v6
	v_mul_f32_e32 v33, v6, v7
	v_mul_f32_e32 v222, v8, v8
	v_mul_f32_e32 v223, v8, v9
	v_mul_f32_e32 v30, v10, v232
	v_mul_f32_e32 v31, v11, v233
	s_waitcnt lgkmcnt(0)
	v_mul_f32_e32 v25, v3, v5
	v_pk_mul_f32 v[30:31], v[30:31], v[30:31] op_sel:[0,1] op_sel_hi:[1,0]
	v_mov_b32_e32 v3, v33
	v_mov_b32_e32 v19, v223
	v_mov_b32_e32 v238, v30
	v_mov_b32_e32 v23, v30
	s_nop 1
	v_permlane32_swap_b32_e32 v238, v23
	s_nop 0
	v_cndmask_b32_e64 v23, v238, v23, s[0:1]
	v_mul_f32_e32 v2, v2, v18
	v_mul_f32_e32 v3, v3, v19
	v_mul_f32_e32 v6, v195, v5
	v_mov_b32_e32 v238, v3
	v_mov_b32_e32 v21, v3
	s_nop 1
	v_permlane32_swap_b32_e32 v238, v21
	s_nop 0
	v_cndmask_b32_e64 v21, v238, v21, s[0:1]
	v_cndmask_b32_e64 v225, v195, v6, s[0:1]
	v_mul_f32_e32 v224, v15, v225
	v_mul_f32_e32 v13, v13, v224
	v_mov_b32_e32 v5, v30
	v_mul_f32_e32 v12, v14, v13
	v_mul_f32_e32 v14, v194, v24
	v_mul_f32_e32 v15, v195, v25
	s_waitcnt lgkmcnt(1)
	v_mul_f32_e32 v4, v4, v22
	v_mul_f32_e32 v5, v5, v23
	v_mov_b32_e32 v234, v231
	v_mov_b32_e32 v235, v17
	v_mov_b32_e32 v231, v16
	v_mul_f32_e32 v16, v4, v14
	v_mul_f32_e32 v17, v5, v15
	s_waitcnt lgkmcnt(0)
	v_mul_f32_e32 v2, v2, v20
	v_mul_f32_e32 v3, v3, v21
	v_mul_f32_e32 v10, v15, v23
	v_mul_f32_e32 v236, v2, v16
	v_mul_f32_e32 v237, v3, v17
	v_mov_b32_e32 v238, v236
	v_mov_b32_e32 v171, v236
	s_nop 1
	v_permlane32_swap_b32_e32 v238, v171
	s_nop 0
	v_cndmask_b32_e64 v171, v238, v171, s[0:1]
	v_mul_f32_e32 v2, v17, v21
	v_cndmask_b32_e64 v3, v17, v2, s[0:1]
	v_mul_f32_e32 v2, v9, v3
	v_mul_f32_e32 v16, v28, v2
	v_mul_f32_e32 v17, v29, v3
	v_mul_f32_e32 v3, v8, v2
	s_waitcnt lgkmcnt(0)
	v_mul_f32_e32 v5, v237, v171
	v_mul_f32_e32 v2, v7, v3
	v_cndmask_b32_e64 v7, v237, v5, s[0:1]
	v_mul_f32_e32 v6, v14, v7
	v_mul_f32_e32 v5, v4, v6
	v_mul_f32_e32 v2, v26, v2
	v_mul_f32_e32 v3, v27, v3
	v_mov_b32_e32 v23, v24
	v_mul_f32_e32 v4, v20, v5
	v_mov_b32_e32 v19, v169
	v_mul_f32_e32 v234, v234, v224
	v_mul_f32_e32 v235, v235, v225
	v_mul_f32_e32 v8, v22, v6
	v_mul_f32_e32 v9, v23, v7
	v_mul_f32_e32 v4, v18, v4
	v_mul_f32_e32 v5, v19, v5
	v_cvt_pk_bf16_f32 v224, v2, v3
	v_cndmask_b32_e64 v3, v15, v10, s[0:1]
	v_cvt_pk_bf16_f32 v222, v4, v5
	v_cvt_pk_bf16_f32 v223, v8, v9
	v_cvt_pk_bf16_f32 v225, v16, v17
	v_mul_f32_e32 v2, v233, v3
	v_mov_b32_e32 v4, v227
	v_mov_b32_e32 v5, v229
	v_mfma_f32_32x32x16_bf16 v[50:65], v[138:141], v[222:225], v[50:65]
	v_mul_f32_e64 v140, v230, v12
	v_mul_f32_e64 v141, v231, v13
	v_mul_f32_e64 v230, v4, v2
	v_mul_f32_e64 v231, v5, v3
	v_mul_f32_e32 v139, v11, v2
	v_mul_f32_e32 v138, v232, v139
	v_mov_b32_e32 v227, v228
	v_mul_f32_e32 v138, v226, v138
	v_mul_f32_e32 v139, v227, v139
	v_cvt_pk_bf16_f32 v140, v140, v141
	v_mfma_f32_32x32x16_bf16 v[34:49], v[218:221], v[222:225], v[34:49]
	v_cvt_pk_bf16_f32 v138, v138, v139
	v_cvt_pk_bf16_f32 v139, v230, v231
	v_cvt_pk_bf16_f32 v141, v234, v235
	s_nop 1
	v_mfma_f32_32x32x16_bf16 v[50:65], v[130:133], v[138:141], v[50:65]
	v_mul_f32_e32 v130, v236, v171
	v_mul_f32_e32 v131, v130, v237
	v_cmp_gt_f32_e32 vcc, s88, v131
	s_cmp_lg_u64 vcc, exec
	v_mfma_f32_32x32x16_bf16 v[34:49], v[134:137], v[138:141], v[34:49]
	s_cbranch_scc0 .LBB0_548
; #define LAS __attribute__((address_space(3)))
; __device__ __forceinline__ void attn_load_k(bf16x8 (&kf)[4], bool in_lds, LAS unsigned char* KL, int kl0, const bf16_t* kg, int ql, int hi) {
;     if (in_lds) { const int r = kl0 + ql; LAS unsigned char* rp = KL + r * 128; const int sw = (r >> 1) & 7;
; #pragma unroll
;         for (int kk = 0; kk < 4; ++kk) kf[kk] = *(const LAS bf16x8*)(rp + (((2 * kk + hi) ^ sw) << 4));
; __device__ __forceinline__ void attn_phase(LAS unsigned char* lds, const bf16_t* Q, const bf16_t* Kb, const bf16_t* VT, const bf16_t* Zs, bf16_t* OZ, int vcu, int G) {
;     ...
;             ATT_TILE(false)
;             if (__all(carry < STOP)) break;
	s_add_i32 s93, s72, -1
	s_sub_i32 s77, s77, 32
	s_sub_i32 s59, s59, 32
	s_cmp_lt_i32 s93, 2
	s_mov_b32 s94, -1
	v_subrev_u32_e32 v165, 32, v165
	v_add_u32_e32 v167, 0xfffff000, v167
	s_cselect_b64 s[80:81], -1, 0
	s_mov_b64 s[82:83], 0
	s_and_b64 vcc, exec, s[80:81]
	v_add_u32_e32 v255, s87, v165
	v_lshrrev_b32_e32 v255, 1, v255
	v_bitop3_b32 v240, v255, v1, 7 bitop3:0x6c
	v_lshl_add_u32 v240, v240, 4, v167
	ds_read_b128 v[240:243], v240
	v_bitop3_b32 v244, v255, v143, 7 bitop3:0x6c
	v_lshl_add_u32 v244, v244, 4, v167
	ds_read_b128 v[244:247], v244
	v_bitop3_b32 v248, v255, v147, 7 bitop3:0x6c
	v_lshl_add_u32 v248, v248, 4, v167
	ds_read_b128 v[248:251], v248
	v_bitop3_b32 v252, v255, v149, 7 bitop3:0x6c
	v_lshl_add_u32 v252, v252, 4, v167
	ds_read_b128 v[252:255], v252
	s_cbranch_vccz .LBB0_545
	s_branch .LBB0_549
